# ssd_scan: B fragments from LDS plus transposed y tiles with 2 dwordx2 stores per lane and chunk
# baseline (speedup 1.0000x reference)
; DI bf16_t f2bf(float f) { return (bf16_t)(pk2(f, 0.f) & 0xffffu); }
; DI void unpack8(const u32x4& w, float* f) { f[0] = bflo(w.x); f[1] = bfhi(w.x); f[2] = bflo(w.y); f[3] = bfhi(w.y); f[4] = bflo(w.z); f[5] = bfhi(w.z); f[6] = bflo(w.w); f[7] = bfhi(w.w); }
; DI void ssd_scan(const Params& P, LAS unsigned char* lds) {
;     ...
;             float cum = dtv * a;
; #pragma unroll
;             for (int of = 1; of < 64; of <<= 1) { const float o = __shfl_up(cum, of); if (lane >= of) cum += o; }
;             const float cl = __shfl(cum, 63); const float wend = __expf(cl - cum) * dtv;
;             { const int p8 = wid * 8; const bf16_t* e = (const bf16_t*)&xw;
; #pragma unroll
;               for (int j = 0; j < 8; ++j) Xt[(p8 + j) * 72 + lane] = e[j]; }
; #pragma unroll
;             for (int i = 0; i < 2; ++i) { const int n8 = (wid + 8 * i) * 8; float f[8]; unpack8(bw[i], f);
; #pragma unroll
;                 for (int j = 0; j < 8; ++j) BWt[(n8 + j) * 72 + lane] = f2bf(f[j] * wend); }
.LBB0_181:
	s_waitcnt vmcnt(2)
	v_bfe_u32 v252, v107, 6, 3
	v_mul_u32_u24_e32 v253, 0x110, v120
	v_lshl_add_u32 v253, v252, 4, v253
	v_add_u32_e32 v253, 0x1a800, v253
	ds_write_b128 v253, v[74:77]
	ds_write_b128 v253, v[50:53] offset:128
	v_and_b32_e32 v252, 1, v252
	v_and_b32_e32 v227, 15, v107
	v_lshl_add_u32 v252, v252, 5, v227
	v_mul_u32_u24_e32 v227, 0x110, v252
	v_bfe_u32 v252, v107, 4, 2
	v_lshl_add_u32 v227, v252, 4, v227
	v_add_u32_e32 v227, 0x1a800, v227
	v_mul_f32_e64 v78, v113, -v166
	ds_bpermute_b32 v79, v130, v78
	s_waitcnt vmcnt(9)
	v_mov_b64_e32 v[92:93], v[32:33]
	v_mov_b64_e32 v[90:91], v[30:31]
	s_and_b32 s17, s19, 1
	s_mul_i32 s23, s17, 0xd400
	s_waitcnt lgkmcnt(0)
	v_fma_f32 v79, v113, -v166, v79
	v_cndmask_b32_e64 v94, v79, v78, s[38:39]
	ds_bpermute_b32 v95, v131, v94
	s_waitcnt vmcnt(8)
	v_mov_b64_e32 v[80:81], v[18:19]
	v_mov_b64_e32 v[78:79], v[16:17]
	v_mov_b64_e32 v[88:89], v[28:29]
	v_mov_b64_e32 v[84:85], v[22:23]
	s_waitcnt lgkmcnt(0)
	v_add_f32_e32 v16, v94, v95
	v_cndmask_b32_e64 v16, v16, v94, s[40:41]
	ds_bpermute_b32 v17, v132, v16
	v_lshlrev_b32_e32 v18, 16, v74
	s_add_i32 s25, s23, 0
	v_mov_b64_e32 v[86:87], v[26:27]
	v_mov_b64_e32 v[82:83], v[20:21]
	s_waitcnt lgkmcnt(0)
	v_add_f32_e32 v17, v16, v17
	v_cndmask_b32_e64 v16, v17, v16, s[42:43]
	ds_bpermute_b32 v17, v133, v16
	v_and_b32_e32 v19, 0xffff0000, v74
	v_lshlrev_b32_e32 v20, 16, v75
	v_lshl_add_u32 v28, v120, 1, s25
	v_add_u32_e32 v29, s3, v28
	s_waitcnt lgkmcnt(0)
	v_add_f32_e32 v17, v16, v17
	v_cndmask_b32_e64 v16, v17, v16, s[44:45]
	ds_bpermute_b32 v17, v134, v16
	v_and_b32_e32 v21, 0xffff0000, v75
	ds_write_b16 v29, v70 offset:9216
	ds_write_b16_d16_hi v29, v70 offset:9360
	ds_write_b16 v29, v71 offset:9504
	ds_write_b16_d16_hi v29, v71 offset:9648
	ds_write_b16 v29, v72 offset:9792
	ds_write_b16_d16_hi v29, v72 offset:9936
	ds_write_b16 v29, v73 offset:10080
	ds_write_b16_d16_hi v29, v73 offset:10224
	s_waitcnt lgkmcnt(8)
	v_add_f32_e32 v17, v16, v17
	v_cndmask_b32_e64 v16, v17, v16, s[46:47]
	ds_bpermute_b32 v17, v135, v16
	v_lshlrev_b32_e32 v22, 16, v76
	v_and_b32_e32 v23, 0xffff0000, v76
	v_lshlrev_b32_e32 v26, 16, v77
	v_and_b32_e32 v27, 0xffff0000, v77
	s_waitcnt lgkmcnt(0)
	v_add_f32_e32 v17, v16, v17
	v_cndmask_b32_e64 v30, v17, v16, s[48:49]
	v_and_b32_e32 v215, 15, v187
	v_lshrrev_b32_e32 v216, 4, v187
	v_lshlrev_b32_e32 v217, 2, v216
	v_sub_u32_e32 v217, v215, v217
	v_lshl_add_u32 v218, v217, 2, v136
	ds_bpermute_b32 v219, v218, v30
	ds_bpermute_b32 v170, v123, v30
	ds_bpermute_b32 v174, v136, v30
	ds_bpermute_b32 v173, v137, v30
	ds_bpermute_b32 v172, v138, v30
	ds_bpermute_b32 v171, v139, v30
	s_waitcnt lgkmcnt(4)
	v_sub_f32_e32 v16, v170, v30
	v_mul_f32_e32 v16, 0x3fb8aa3b, v16
	v_exp_f32_e32 v16, v16
	s_xor_b32 s17, s17, 1
	v_add_u32_e32 v118, s18, v169
	v_mov_b64_e32 v[176:177], s[6:7]
	v_mul_f32_e32 v16, v113, v16
	v_mul_f32_e32 v17, v16, v18
	v_mul_f32_e32 v18, v16, v19
	v_mul_f32_e32 v19, v16, v20
	v_cvt_pk_bf16_f32 v17, v17, s0
	v_cvt_pk_bf16_f32 v18, v18, s0
	ds_write_b16 v29, v17 offset:35840
	ds_write_b16 v29, v18 offset:35984
	v_cvt_pk_bf16_f32 v17, v19, s0
	ds_write_b16 v29, v17 offset:36128
	v_mul_f32_e32 v17, v16, v21
	v_cvt_pk_bf16_f32 v17, v17, s0
	ds_write_b16 v29, v17 offset:36272
	v_mul_f32_e32 v17, v16, v22
	v_cvt_pk_bf16_f32 v17, v17, s0
	ds_write_b16 v29, v17 offset:36416
	v_mul_f32_e32 v17, v16, v23
	v_cvt_pk_bf16_f32 v17, v17, s0
	ds_write_b16 v29, v17 offset:36560
	v_mul_f32_e32 v17, v16, v26
	v_cvt_pk_bf16_f32 v17, v17, s0
	ds_write_b16 v29, v17 offset:36704
	v_mul_f32_e32 v17, v16, v27
	v_cvt_pk_bf16_f32 v17, v17, s0
	ds_write_b16 v29, v17 offset:36848
	v_lshlrev_b32_e32 v17, 16, v50
	v_mul_f32_e32 v17, v16, v17
	v_and_b32_e32 v18, 0xffff0000, v50
	v_cvt_pk_bf16_f32 v17, v17, s0
	v_add_u32_e32 v27, s21, v28
	ds_write_b16 v27, v17 offset:35840
	v_mul_f32_e32 v17, v16, v18
	v_lshlrev_b32_e32 v19, 16, v51
	v_cvt_pk_bf16_f32 v17, v17, s0
	ds_write_b16 v29, v17 offset:45200
	v_mul_f32_e32 v17, v16, v19
	v_and_b32_e32 v20, 0xffff0000, v51
	v_cvt_pk_bf16_f32 v17, v17, s0
	ds_write_b16 v29, v17 offset:45344
	v_mul_f32_e32 v17, v16, v20
	v_lshlrev_b32_e32 v21, 16, v52
	v_cvt_pk_bf16_f32 v17, v17, s0
	ds_write_b16 v29, v17 offset:45488
	v_mul_f32_e32 v17, v16, v21
	v_and_b32_e32 v22, 0xffff0000, v52
	v_cvt_pk_bf16_f32 v17, v17, s0
	ds_write_b16 v29, v17 offset:45632
	v_mul_f32_e32 v17, v16, v22
	v_lshlrev_b32_e32 v23, 16, v53
	v_cvt_pk_bf16_f32 v17, v17, s0
	v_and_b32_e32 v26, 0xffff0000, v53
	ds_write_b16 v29, v17 offset:45776
	v_mul_f32_e32 v17, v16, v23
	v_cvt_pk_bf16_f32 v17, v17, s0
	v_mul_f32_e32 v16, v16, v26
	ds_write_b16 v29, v17 offset:45920
	v_cvt_pk_bf16_f32 v20, v16, s0
	s_waitcnt vmcnt(0)
	s_waitcnt lgkmcnt(0)
	s_barrier
; #define LAS __attribute__((address_space(3)))
; DI bf16_t f2bf(float f) { return (bf16_t)(pk2(f, 0.f) & 0xffffu); }
; #define LDS_BARRIER() do { asm volatile("s_waitcnt lgkmcnt(0)" ::: "memory"); __builtin_amdgcn_s_barrier(); asm volatile("" ::: "memory"); } while (0)
; #define MFMA16(a, b, c) __builtin_amdgcn_mfma_f32_16x16x32_bf16((a), (b), (c), 0, 0, 0)
; DI void ssd_scan(const Params& P, LAS unsigned char* lds) {
;     ...
; #pragma unroll
;             for (int j = 0; j < 4; ++j) cumt[j] = __shfl(cum, 16 * mb + 4 * fq + j);
; #pragma unroll
;             for (int i = 0; i < 2; ++i) { const int nb = 2 * hb + i; f32x4 sc = {0.f, 0.f, 0.f, 0.f};
; #pragma unroll
;                 for (int ks = 0; ks < 4; ++ks) sc = MFMA16(ca[ks], bbf[i][ks], sc);
;                 const int s = 16 * nb + fr; const float cums = __shfl(cum, s), dts = __shfl(dtv, s);
; #pragma unroll
;                 for (int j = 0; j < 4; ++j) { const int t = 16 * mb + 4 * fq + j; Pm[t * 72 + s] = f2bf(s <= t ? sc[j] * __expf(cumt[j] - cums) * dts : 0.f); } }
;             LDS_BARRIER();
;             float dtn = dtv; bf16x8 cn[4];
; #pragma unroll
;             for (int ks = 0; ks < 4; ++ks) cn[ks] = ca[ks];
;             if (n + 1 < 32) SSD_LOAD(row0 + 64, dtn, cn);
;             f32x4 yi[2], ye[2];
; #pragma unroll
;             for (int i = 0; i < 2; ++i) { yi[i] = (f32x4){0.f, 0.f, 0.f, 0.f}; ye[i] = (f32x4){0.f, 0.f, 0.f, 0.f}; }
; #pragma unroll
;             for (int k2 = 0; k2 < 2; ++k2) { const bf16x8 am = *(const LAS bf16x8*)(Pm + (16 * mb + fr) * 72 + 32 * k2 + 8 * fq);
; #pragma unroll
;                 for (int i = 0; i < 2; ++i) { const bf16x8 bb = *(const LAS bf16x8*)(Xt + (16 * (2 * hb + i) + fr) * 72 + 32 * k2 + 8 * fq); yi[i] = MFMA16(am, bb, yi[i]); } }
	ds_read_b128 v[54:57], v227
	ds_read_b128 v[58:61], v227 offset:64
	ds_read_b128 v[66:69], v227 offset:128
	ds_read_b128 v[62:65], v227 offset:192
	ds_read_b128 v[46:49], v227 offset:4352
	ds_read_b128 v[38:41], v227 offset:4416
	ds_read_b128 v[42:45], v227 offset:4480
	ds_read_b128 v[34:37], v227 offset:4544
	s_waitcnt lgkmcnt(0)
	s_waitcnt vmcnt(5)
	v_mfma_f32_16x16x32_bf16 v[16:19], v[90:93], v[54:57], 0
	ds_write_b16 v29, v20 offset:46064
	ds_bpermute_b32 v20, v140, v30
	ds_bpermute_b32 v26, v140, v113
	v_mfma_f32_16x16x32_bf16 v[16:19], v[86:89], v[58:61], v[16:19]
	v_add3_u32 v27, s25, v102, v141
	s_mul_i32 s23, s17, 0xd400
	s_waitcnt lgkmcnt(1)
	v_sub_f32_e32 v21, v174, v20
	v_mfma_f32_16x16x32_bf16 v[16:19], v[82:85], v[66:69], v[16:19]
	v_mul_f32_e32 v21, 0x3fb8aa3b, v21
	v_exp_f32_e32 v21, v21
	s_mov_b32 s17, s37
	s_waitcnt vmcnt(4)
	v_mfma_f32_16x16x32_bf16 v[16:19], v[78:81], v[62:65], v[16:19]
	v_add_u32_e32 v175, s25, v24
	v_add_u32_e32 v58, v175, v146
	v_add3_u32 v214, s25, v126, v148
	v_ashrrev_i32_e32 v119, 31, v118
	s_add_i32 s19, s19, 1
	s_nop 2
	v_mul_f32_e32 v16, v16, v21
	v_sub_f32_e32 v21, v173, v20
	v_mul_f32_e32 v21, 0x3fb8aa3b, v21
	v_exp_f32_e32 v21, v21
	s_waitcnt lgkmcnt(0)
	v_mul_f32_e32 v16, v16, v26
	v_cvt_pk_bf16_f32 v16, v16, s0
	v_cndmask_b32_e64 v16, v16, 0, s[50:51]
	ds_write_b16 v27, v16
	v_mul_f32_e32 v16, v17, v21
	v_sub_f32_e32 v17, v172, v20
	v_mul_f32_e32 v17, 0x3fb8aa3b, v17
	v_exp_f32_e32 v17, v17
	v_mul_f32_e32 v16, v16, v26
	v_cvt_pk_bf16_f32 v16, v16, s0
	v_cndmask_b32_e64 v16, v16, 0, s[52:53]
	ds_write_b16 v27, v16 offset:144
	v_mul_f32_e32 v16, v18, v17
	v_sub_f32_e32 v17, v171, v20
	v_mul_f32_e32 v17, 0x3fb8aa3b, v17
	v_exp_f32_e32 v17, v17
	v_mul_f32_e32 v16, v16, v26
	v_cvt_pk_bf16_f32 v16, v16, s0
	s_waitcnt vmcnt(1)
	v_mfma_f32_16x16x32_bf16 v[20:23], v[90:93], v[46:49], 0
	v_cndmask_b32_e64 v16, v16, 0, s[54:55]
	ds_write_b16 v27, v16 offset:288
	v_mul_f32_e32 v16, v19, v17
	v_mul_f32_e32 v16, v16, v26
	v_cvt_pk_bf16_f32 v26, v16, s0
	v_mfma_f32_16x16x32_bf16 v[16:19], v[86:89], v[38:41], v[20:23]
	v_add_u32_e32 v46, v175, v125
	s_nop 1
	ds_bpermute_b32 v20, v145, v30
	v_mfma_f32_16x16x32_bf16 v[16:19], v[82:85], v[42:45], v[16:19]
	v_cndmask_b32_e64 v21, v26, 0, s[56:57]
	ds_write_b16 v27, v21 offset:432
	ds_bpermute_b32 v21, v145, v113
	s_waitcnt lgkmcnt(2)
	v_sub_f32_e32 v22, v174, v20
	v_mul_f32_e32 v22, 0x3fb8aa3b, v22
	v_exp_f32_e32 v22, v22
	s_waitcnt vmcnt(0)
	v_mfma_f32_16x16x32_bf16 v[16:19], v[78:81], v[34:37], v[16:19]
	v_add_u32_e32 v113, s18, v165
	v_add_u32_e32 v38, 64, v113
	v_mad_i64_i32 v[42:43], s[66:67], v38, s87, v[176:177]
	v_lshl_add_u64 v[42:43], v[42:43], 0, s[16:17]
	s_nop 3
	v_mul_f32_e32 v16, v16, v22
	v_sub_f32_e32 v22, v173, v20
	v_mul_f32_e32 v22, 0x3fb8aa3b, v22
	v_exp_f32_e32 v22, v22
	s_waitcnt lgkmcnt(0)
	v_mul_f32_e32 v16, v16, v21
	v_cvt_pk_bf16_f32 v16, v16, s0
	v_cndmask_b32_e64 v16, v16, 0, s[58:59]
	ds_write_b16 v27, v16 offset:32
	v_mul_f32_e32 v16, v17, v22
	v_sub_f32_e32 v17, v172, v20
	v_mul_f32_e32 v17, 0x3fb8aa3b, v17
	v_exp_f32_e32 v17, v17
	v_mul_f32_e32 v16, v16, v21
	v_cvt_pk_bf16_f32 v16, v16, s0
	v_cndmask_b32_e64 v16, v16, 0, s[60:61]
	ds_write_b16 v27, v16 offset:176
	v_mul_f32_e32 v16, v18, v17
	v_sub_f32_e32 v17, v171, v20
	v_mul_f32_e32 v17, 0x3fb8aa3b, v17
	v_exp_f32_e32 v17, v17
	v_mul_f32_e32 v16, v16, v21
	v_cvt_pk_bf16_f32 v16, v16, s0
	v_cndmask_b32_e64 v16, v16, 0, s[62:63]
	ds_write_b16 v27, v16 offset:320
	v_mul_f32_e32 v16, v19, v17
	v_mul_f32_e32 v16, v16, v21
	v_cvt_pk_bf16_f32 v16, v16, s0
	v_cndmask_b32_e64 v16, v16, 0, s[64:65]
	ds_write_b16 v27, v16 offset:464
	v_mad_i64_i32 v[16:17], s[66:67], v118, s87, v[176:177]
	v_lshl_add_u64 v[18:19], v[16:17], 0, s[36:37]
	v_lshl_add_u64 v[16:17], v[16:17], 0, s[16:17]
	s_waitcnt lgkmcnt(0)
	s_barrier
	v_lshl_add_u64 v[18:19], v[18:19], 0, s[12:13]
	v_lshl_add_u64 v[16:17], v[16:17], 0, s[12:13]
	global_load_dwordx4 v[70:73], v[18:19], off
	v_lshl_add_u64 v[18:19], v[16:17], 0, s[70:71]
	v_add_co_u32_e32 v16, vcc, s86, v16
	v_lshl_add_u64 v[54:55], v[42:43], 0, v[24:25]
	s_nop 0
	v_addc_co_u32_e32 v17, vcc, 0, v17, vcc
	global_load_dwordx4 v[74:77], v[16:17], off
	global_load_dwordx4 v[50:53], v[18:19], off offset:128
	v_add_u32_e32 v16, s18, v168
	v_mad_i64_i32 v[16:17], s[66:67], v16, s87, v[176:177]
	v_lshl_add_u64 v[16:17], v[16:17], 0, s[16:17]
	v_lshl_add_u64 v[16:17], v[16:17], 0, v[24:25]
	v_lshl_add_u64 v[18:19], v[16:17], 0, s[96:97]
	v_add_co_u32_e32 v16, vcc, s86, v16
	v_lshl_add_u64 v[178:179], v[54:55], 0, s[70:71]
	s_nop 0
	v_addc_co_u32_e32 v17, vcc, 0, v17, vcc
	global_load_dwordx4 v[30:33], v[16:17], off offset:1024
	global_load_dwordx4 v[26:29], v[18:19], off offset:64
	global_load_dwordx4 v[20:23], v[18:19], off offset:128
	s_nop 0
	global_load_dwordx4 v[16:19], v[18:19], off offset:192
	ds_read_b128 v[34:37], v46
	ds_read_b128 v[38:41], v58 offset:9216
	ds_read_b128 v[42:45], v58 offset:11520
	ds_read_b128 v[62:65], v58 offset:11584
	ds_read_b128 v[46:49], v46 offset:64
	s_waitcnt lgkmcnt(3)
	v_mfma_f32_16x16x32_bf16 v[38:41], v[38:41], v[34:37], 0
	v_add_co_u32_e32 v54, vcc, s86, v54
	v_lshlrev_b64 v[118:119], 7, v[118:119]
	s_waitcnt lgkmcnt(2)
	v_mfma_f32_16x16x32_bf16 v[34:37], v[42:45], v[34:37], 0
	ds_read_b128 v[42:45], v58 offset:9280
	v_addc_co_u32_e32 v55, vcc, 0, v55, vcc
	s_waitcnt lgkmcnt(0)
	v_mfma_f32_16x16x32_bf16 v[98:101], v[42:45], v[46:49], v[38:41]
	v_add_u32_e32 v42, 0x50, v113
	s_nop 1
	ds_read_b128 v[38:41], v214 offset:18432
	v_mad_i64_i32 v[42:43], s[66:67], v42, s87, v[176:177]
	s_nop 0
	v_mfma_f32_16x16x32_bf16 v[94:97], v[62:65], v[46:49], v[34:37]
	s_nop 0
	s_nop 0
	s_nop 0
	v_lshl_add_u64 v[46:47], v[42:43], 0, s[16:17]
	s_waitcnt lgkmcnt(0)
; #define LAS __attribute__((address_space(3)))
; DI unsigned pk2(float lo, float hi) { const f32x2v v = {lo, hi}; const bf16x2v b = __builtin_convertvector(v, bf16x2v); return __builtin_bit_cast(unsigned, b); }
; DI float bf2f(bf16_t b) { return __uint_as_float(((unsigned)b) << 16); }
; DI bf16_t f2bf(float f) { return (bf16_t)(pk2(f, 0.f) & 0xffffu); }
; #define MFMA16(a, b, c) __builtin_amdgcn_mfma_f32_16x16x32_bf16((a), (b), (c), 0, 0, 0)
; DI void ssd_scan(const Params& P, LAS unsigned char* lds) {
;     ...
; #pragma unroll
;             for (int ks = 0; ks < 4; ++ks)
; #pragma unroll
;                 for (int i = 0; i < 2; ++i) { const bf16x8 bb = *(const LAS bf16x8*)(Sb + (16 * (2 * hb + i) + fr) * 136 + 32 * ks + 8 * fq); ye[i] = MFMA16(ca[ks], bb, ye[i]); }
; #pragma unroll
;             for (int j = 0; j < 4; ++j) { const int tl = 16 * mb + 4 * fq + j, row = row0 + tl; const float ec = __expf(cumt[j]);
; #pragma unroll
;                 for (int i = 0; i < 2; ++i) { const int p = 16 * (2 * hb + i) + fr; const float xv = bf2f(Xt[p * 72 + tl]);
;                     YB[(size_t)row * 2048 + h * 64 + p] = f2bf(yi[i][j] + ec * ye[i][j] + dsk * xv); } }
;             { const float ecl = __expf(cl);
; #pragma unroll
;               for (int i = 0; i < 4; ++i) Sacc[i] *= ecl; }
; #pragma unroll
;             for (int k2 = 0; k2 < 2; ++k2) { const bf16x8 am = *(const LAS bf16x8*)(BWt + (16 * wid + fr) * 72 + 32 * k2 + 8 * fq);
; #pragma unroll
;                 for (int i = 0; i < 4; ++i) { const bf16x8 bb = *(const LAS bf16x8*)(Xt + (16 * i + fr) * 72 + 32 * k2 + 8 * fq); Sacc[i] = MFMA16(am, bb, Sacc[i]); } }
; #pragma unroll
;             for (int i = 0; i < 4; ++i) { u32x2 w; w.x = pk2(Sacc[i][0], Sacc[i][1]); w.y = pk2(Sacc[i][2], Sacc[i][3]); *(LAS u32x2*)(Sbn + (16 * i + fr) * 136 + 16 * wid + 4 * fq) = w; }
;             dtv = dtn;
; #pragma unroll
;             for (int ks = 0; ks < 4; ++ks) ca[ks] = cn[ks];
	v_mfma_f32_16x16x32_bf16 v[34:37], v[38:41], v[90:93], 0
	ds_read_b128 v[38:41], v214 offset:22784
	ds_read_b128 v[42:45], v214 offset:18496
	v_lshl_add_u64 v[118:119], s[14:15], 0, v[118:119]
	s_waitcnt lgkmcnt(1)
	v_mfma_f32_16x16x32_bf16 v[38:41], v[38:41], v[90:93], 0
	v_lshl_add_u64 v[90:91], v[46:47], 0, v[24:25]
	ds_read_b128 v[46:49], v214 offset:22848
	v_add_co_u32_e32 v180, vcc, s86, v90
	s_waitcnt lgkmcnt(1)
	v_mfma_f32_16x16x32_bf16 v[34:37], v[42:45], v[86:89], v[34:37]
	ds_read_b128 v[42:45], v214 offset:18560
	v_lshl_add_u64 v[212:213], v[90:91], 0, s[70:71]
	v_addc_co_u32_e32 v181, vcc, 0, v91, vcc
	s_waitcnt lgkmcnt(1)
	v_mfma_f32_16x16x32_bf16 v[86:89], v[46:49], v[86:89], v[38:41]
	ds_read_b128 v[90:93], v214 offset:22912
	s_nop 0
	s_nop 0
	s_nop 0
	ds_read_b128 v[180:183], v214 offset:18624
	s_waitcnt lgkmcnt(2)
	v_mfma_f32_16x16x32_bf16 v[176:179], v[42:45], v[82:85], v[34:37]
	s_nop 0
	s_nop 1
	s_nop 0
	global_load_dword v113, v[118:119], off
	s_waitcnt lgkmcnt(1)
	v_mfma_f32_16x16x32_bf16 v[82:85], v[90:93], v[82:85], v[86:89]
	s_nop 2
	ds_read_b128 v[86:89], v214 offset:22976
	s_waitcnt lgkmcnt(1)
	v_mfma_f32_16x16x32_bf16 v[90:93], v[180:183], v[78:81], v[176:179]
	s_waitcnt lgkmcnt(0)
	v_mfma_f32_16x16x32_bf16 v[78:81], v[86:89], v[78:81], v[82:85]
	v_mul_f32_e32 v220, 0x3fb8aa3b, v219
	v_exp_f32_e32 v220, v220
	v_lshlrev_b32_e32 v222, 1, v124
	v_add3_u32 v222, s25, v222, v146
	v_mul_i32_i24_e32 v221, 0xffffff72, v217
	v_add_u32_e32 v221, v222, v221
	ds_read_u16 v223, v221 offset:9216
	ds_read_u16 v224, v221 offset:9360
	ds_read_u16 v225, v221 offset:9504
	ds_read_u16 v226, v221 offset:9648
	ds_read_u16 v248, v221 offset:11520
	ds_read_u16 v249, v221 offset:11664
	ds_read_u16 v250, v221 offset:11808
	ds_read_u16 v251, v221 offset:11952
	v_add_u32_e32 v228, s18, v109
	v_add_u32_e32 v228, v228, v217
	v_ashrrev_i32_e32 v229, 31, v228
	v_lshlrev_b64 v[228:229], 12, v[228:229]
	v_lshlrev_b32_e32 v230, 1, v217
	v_sub_u32_e32 v230, 0, v230
	v_ashrrev_i32_e32 v231, 31, v230
	v_lshl_add_u64 v[228:229], v[228:229], 0, v[230:231]
	v_lshl_add_u64 v[232:233], v[114:115], 0, v[228:229]
	v_lshl_add_u64 v[234:235], v[116:117], 0, v[228:229]
	s_add_i32 s18, s18, 64
	s_cmpk_eq_i32 s18, 0x7c0
	v_fma_f32 v240, v220, v90, v98
	v_fma_f32 v241, v220, v91, v99
	v_fma_f32 v242, v220, v92, v100
	v_fma_f32 v243, v220, v93, v101
	v_fma_f32 v244, v220, v78, v94
	v_fma_f32 v245, v220, v79, v95
	v_fma_f32 v246, v220, v80, v96
	v_fma_f32 v247, v220, v81, v97
	s_waitcnt lgkmcnt(0)
	v_lshlrev_b32_e32 v223, 16, v223
	v_lshlrev_b32_e32 v224, 16, v224
	v_lshlrev_b32_e32 v225, 16, v225
	v_lshlrev_b32_e32 v226, 16, v226
	v_lshlrev_b32_e32 v248, 16, v248
	v_lshlrev_b32_e32 v249, 16, v249
	v_lshlrev_b32_e32 v250, 16, v250
	v_lshlrev_b32_e32 v251, 16, v251
	v_fmac_f32_e32 v240, v111, v223
	v_fmac_f32_e32 v241, v111, v224
	v_fmac_f32_e32 v242, v111, v225
	v_fmac_f32_e32 v243, v111, v226
	v_fmac_f32_e32 v244, v111, v248
	v_fmac_f32_e32 v245, v111, v249
	v_fmac_f32_e32 v246, v111, v250
	v_fmac_f32_e32 v247, v111, v251
	v_cvt_pk_bf16_f32 v236, v240, v241
	v_cvt_pk_bf16_f32 v237, v242, v243
	v_cvt_pk_bf16_f32 v238, v244, v245
	v_cvt_pk_bf16_f32 v239, v246, v247
	global_store_dwordx2 v[232:233], v[236:237], off
	global_store_dwordx2 v[234:235], v[238:239], off
	v_add_u32_e32 v96, v175, v127
	ds_read_b128 v[84:87], v96 offset:35840
	s_nop 0
	s_nop 0
	v_mul_f32_e32 v80, 0x3fb8aa3b, v170
	v_add_u32_e32 v119, v175, v149
	v_exp_f32_e32 v80, v80
	ds_read_b128 v[88:91], v119 offset:9216
	ds_read_b128 v[92:95], v119 offset:11520
	s_nop 0
	v_pk_mul_f32 v[2:3], v[2:3], v[80:81] op_sel_hi:[1,0]
	v_pk_mul_f32 v[0:1], v[0:1], v[80:81] op_sel_hi:[1,0]
	v_pk_mul_f32 v[6:7], v[6:7], v[80:81] op_sel_hi:[1,0]
	v_pk_mul_f32 v[4:5], v[4:5], v[80:81] op_sel_hi:[1,0]
	s_waitcnt lgkmcnt(1)
	v_mfma_f32_16x16x32_bf16 v[0:3], v[84:87], v[88:91], v[0:3]
	ds_read_b128 v[88:91], v119 offset:13824
	v_pk_mul_f32 v[14:15], v[14:15], v[80:81] op_sel_hi:[1,0]
	v_pk_mul_f32 v[12:13], v[12:13], v[80:81] op_sel_hi:[1,0]
	s_waitcnt lgkmcnt(1)
	v_mfma_f32_16x16x32_bf16 v[4:7], v[84:87], v[92:95], v[4:7]
	ds_read_b128 v[92:95], v119 offset:16128
	ds_read_b128 v[98:101], v96 offset:35904
	s_nop 0
	v_pk_mul_f32 v[10:11], v[10:11], v[80:81] op_sel_hi:[1,0]
	s_waitcnt lgkmcnt(2)
	v_mfma_f32_16x16x32_bf16 v[12:15], v[84:87], v[88:91], v[12:15]
	ds_read_b128 v[88:91], v119 offset:9280
	v_pk_mul_f32 v[8:9], v[8:9], v[80:81] op_sel_hi:[1,0]
	s_nop 0
	s_waitcnt lgkmcnt(2)
	v_mfma_f32_16x16x32_bf16 v[8:11], v[84:87], v[92:95], v[8:11]
	s_nop 0
	s_nop 0
	ds_read_b128 v[84:87], v119 offset:11584
	s_waitcnt lgkmcnt(1)
	v_mfma_f32_16x16x32_bf16 v[0:3], v[98:101], v[88:91], v[0:3]
	s_nop 0
	s_nop 0
	ds_read_b128 v[88:91], v119 offset:13888
	s_nop 0
	ds_read_b128 v[78:81], v119 offset:16192
	s_waitcnt lgkmcnt(2)
	v_mfma_f32_16x16x32_bf16 v[4:7], v[98:101], v[84:87], v[4:7]
	s_nop 0
	s_nop 0
	s_nop 0
	s_waitcnt lgkmcnt(1)
	v_mfma_f32_16x16x32_bf16 v[12:15], v[98:101], v[88:91], v[12:15]
	s_waitcnt lgkmcnt(0)
	v_mfma_f32_16x16x32_bf16 v[8:11], v[98:101], v[78:81], v[8:11]
	v_cvt_pk_bf16_f32 v78, v0, v1
	v_cvt_pk_bf16_f32 v79, v2, v3
	v_add3_u32 v80, v154, s23, v150
	ds_write_b64 v80, v[78:79] offset:18432
	v_cvt_pk_bf16_f32 v78, v4, v5
	v_cvt_pk_bf16_f32 v79, v6, v7
	ds_write_b64 v80, v[78:79] offset:22784
	v_cvt_pk_bf16_f32 v78, v12, v13
	v_cvt_pk_bf16_f32 v79, v14, v15
	ds_write_b64 v80, v[78:79] offset:27136
	v_cvt_pk_bf16_f32 v78, v8, v9
	v_cvt_pk_bf16_f32 v79, v10, v11
	ds_write_b64 v80, v[78:79] offset:31488
	s_cbranch_scc0 .LBB0_181
; #define LAS __attribute__((address_space(3)))
; DI bf16_t f2bf(float f) { return (bf16_t)(pk2(f, 0.f) & 0xffffu); }
; DI void unpack8(const u32x4& w, float* f) { f[0] = bflo(w.x); f[1] = bfhi(w.x); f[2] = bflo(w.y); f[3] = bfhi(w.y); f[4] = bflo(w.z); f[5] = bfhi(w.z); f[6] = bflo(w.w); f[7] = bfhi(w.w); }
; #define MFMA16(a, b, c) __builtin_amdgcn_mfma_f32_16x16x32_bf16((a), (b), (c), 0, 0, 0)
; DI void ssd_scan(const Params& P, LAS unsigned char* lds) {
;     ...
;         for (int n = 0; n < 32; ++n) {
;             const int row0 = b * 2048 + 64 * n;
;             LAS unsigned char* sb_ = lds + (n & 1) * SSET; LAS unsigned char* so_ = lds + ((n & 1) ^ 1) * SSET;
;             LAS bf16_t* Pm = (LAS bf16_t*)sb_; LAS bf16_t* Xt = (LAS bf16_t*)(sb_ + 9216); LAS bf16_t* Sb = (LAS bf16_t*)(sb_ + 18432); LAS bf16_t* BWt = (LAS bf16_t*)(sb_ + 35840);
;             LAS bf16_t* Sbn = (LAS bf16_t*)(so_ + 18432);
;             float cum = dtv * a;
; #pragma unroll
;             for (int of = 1; of < 64; of <<= 1) { const float o = __shfl_up(cum, of); if (lane >= of) cum += o; }
;             const float cl = __shfl(cum, 63); const float wend = __expf(cl - cum) * dtv;
;             { const int p8 = wid * 8; const bf16_t* e = (const bf16_t*)&xw;
; #pragma unroll
;               for (int j = 0; j < 8; ++j) Xt[(p8 + j) * 72 + lane] = e[j]; }
; #pragma unroll
;             for (int i = 0; i < 2; ++i) { const int n8 = (wid + 8 * i) * 8; float f[8]; unpack8(bw[i], f);
; #pragma unroll
;                 for (int j = 0; j < 8; ++j) BWt[(n8 + j) * 72 + lane] = f2bf(f[j] * wend); }
;             float cumt[4];
; #pragma unroll
;             for (int j = 0; j < 4; ++j) cumt[j] = __shfl(cum, 16 * mb + 4 * fq + j);
; #pragma unroll
;             for (int i = 0; i < 2; ++i) { const int nb = 2 * hb + i; f32x4 sc = {0.f, 0.f, 0.f, 0.f};
; #pragma unroll
;                 for (int ks = 0; ks < 4; ++ks) sc = MFMA16(ca[ks], bbf[i][ks], sc);
;                 const int s = 16 * nb + fr; const float cums = __shfl(cum, s), dts = __shfl(dtv, s);
; #pragma unroll
;                 for (int j = 0; j < 4; ++j) { const int t = 16 * mb + 4 * fq + j; Pm[t * 72 + s] = f2bf(s <= t ? sc[j] * __expf(cumt[j] - cums) * dts : 0.f); } }
	s_waitcnt vmcnt(2)
	v_bfe_u32 v252, v107, 6, 3
	v_mul_u32_u24_e32 v253, 0x110, v120
	v_lshl_add_u32 v253, v252, 4, v253
	v_add_u32_e32 v253, 0x1a800, v253
	ds_write_b128 v253, v[74:77]
	ds_write_b128 v253, v[50:53] offset:128
	v_and_b32_e32 v252, 1, v252
	v_and_b32_e32 v227, 15, v107
	v_lshl_add_u32 v252, v252, 5, v227
	v_mul_u32_u24_e32 v227, 0x110, v252
	v_bfe_u32 v252, v107, 4, 2
	v_lshl_add_u32 v227, v252, 4, v227
	v_add_u32_e32 v227, 0x1a800, v227
	s_waitcnt vmcnt(0)
	s_waitcnt lgkmcnt(0)
	s_barrier
	ds_read_b128 v[54:57], v227
	ds_read_b128 v[58:61], v227 offset:64
	ds_read_b128 v[66:69], v227 offset:128
	ds_read_b128 v[62:65], v227 offset:192
	ds_read_b128 v[46:49], v227 offset:4352
	ds_read_b128 v[38:41], v227 offset:4416
	ds_read_b128 v[42:45], v227 offset:4480
	ds_read_b128 v[34:37], v227 offset:4544
	s_waitcnt lgkmcnt(0)
	v_mul_f32_e64 v78, v113, -v166
	ds_bpermute_b32 v79, v130, v78
	ds_write_b16 v159, v70 offset:63488
	ds_write_b16_d16_hi v159, v70 offset:63632
	ds_write_b16 v159, v71 offset:63776
	ds_write_b16_d16_hi v159, v71 offset:63920
	ds_write_b16 v159, v72 offset:64064
	ds_write_b16_d16_hi v159, v72 offset:64208
	ds_write_b16 v159, v73 offset:64352
	ds_write_b16_d16_hi v159, v73 offset:64496
	v_lshlrev_b32_e32 v71, 16, v74
	v_and_b32_e32 v72, 0xffff0000, v74
	v_add_u32_e32 v81, s3, v151
	s_waitcnt lgkmcnt(8)
	v_fma_f32 v79, v113, -v166, v79
	v_cndmask_b32_e64 v78, v79, v78, s[38:39]
	ds_bpermute_b32 v79, v131, v78
	v_lshlrev_b32_e32 v73, 16, v75
	v_and_b32_e32 v74, 0xffff0000, v75
	v_lshlrev_b32_e32 v75, 16, v76
	v_and_b32_e32 v76, 0xffff0000, v76
	s_waitcnt lgkmcnt(0)
	v_add_f32_e32 v79, v78, v79
	v_cndmask_b32_e64 v78, v79, v78, s[40:41]
	ds_bpermute_b32 v79, v132, v78
	v_mfma_f32_16x16x32_bf16 v[46:49], v[30:33], v[46:49], 0
	s_or_b32 s5, s5, 0x7c0
	s_waitcnt lgkmcnt(0)
	v_add_f32_e32 v79, v78, v79
	v_cndmask_b32_e64 v78, v79, v78, s[42:43]
	ds_bpermute_b32 v79, v133, v78
	v_mfma_f32_16x16x32_bf16 v[38:41], v[26:29], v[38:41], v[46:49]
	s_waitcnt lgkmcnt(0)
	v_add_f32_e32 v79, v78, v79
	v_cndmask_b32_e64 v78, v79, v78, s[44:45]
	ds_bpermute_b32 v79, v134, v78
	v_mfma_f32_16x16x32_bf16 v[54:57], v[30:33], v[54:57], 0
	s_waitcnt lgkmcnt(0)
	v_add_f32_e32 v79, v78, v79
	v_cndmask_b32_e64 v78, v79, v78, s[46:47]
	ds_bpermute_b32 v79, v135, v78
	v_mfma_f32_16x16x32_bf16 v[38:41], v[20:23], v[42:45], v[38:41]
	s_waitcnt lgkmcnt(0)
	v_add_f32_e32 v79, v78, v79
	v_cndmask_b32_e64 v79, v79, v78, s[48:49]
	ds_bpermute_b32 v78, v123, v79
	v_mfma_f32_16x16x32_bf16 v[54:57], v[26:29], v[58:61], v[54:57]
	ds_bpermute_b32 v58, v140, v79
	ds_bpermute_b32 v59, v140, v113
	s_waitcnt lgkmcnt(2)
	v_sub_f32_e32 v80, v78, v79
	v_mul_f32_e32 v80, 0x3fb8aa3b, v80
	v_exp_f32_e32 v80, v80
	v_mfma_f32_16x16x32_bf16 v[34:37], v[16:19], v[34:37], v[38:41]
	v_mul_f32_e32 v70, v113, v80
	v_mul_f32_e32 v71, v70, v71
	v_cvt_pk_bf16_f32 v71, v71, s0
	ds_write_b16 v81, v71
	v_mul_f32_e32 v71, v70, v72
	v_cvt_pk_bf16_f32 v71, v71, s0
	ds_write_b16 v81, v71 offset:144
	v_mul_f32_e32 v71, v70, v73
	v_cvt_pk_bf16_f32 v71, v71, s0
	ds_write_b16 v81, v71 offset:288
	v_mul_f32_e32 v71, v70, v74
	v_cvt_pk_bf16_f32 v71, v71, s0
	ds_write_b16 v81, v71 offset:432
	v_mul_f32_e32 v71, v70, v75
	v_cvt_pk_bf16_f32 v71, v71, s0
	ds_write_b16 v81, v71 offset:576
	v_mul_f32_e32 v71, v70, v76
	v_lshlrev_b32_e32 v80, 16, v77
	v_cvt_pk_bf16_f32 v71, v71, s0
	ds_write_b16 v81, v71 offset:720
	v_mul_f32_e32 v71, v70, v80
	v_and_b32_e32 v77, 0xffff0000, v77
	v_cvt_pk_bf16_f32 v71, v71, s0
	ds_write_b16 v81, v71 offset:864
	v_mul_f32_e32 v71, v70, v77
	v_cvt_pk_bf16_f32 v71, v71, s0
	ds_write_b16 v81, v71 offset:1008
	v_lshlrev_b32_e32 v71, 16, v50
	v_and_b32_e32 v50, 0xffff0000, v50
	v_mul_f32_e32 v50, v70, v50
	v_lshlrev_b32_e32 v72, 16, v51
	v_cvt_pk_bf16_f32 v50, v50, s0
	ds_write_b16 v81, v50 offset:9360
	v_mul_f32_e32 v50, v70, v72
	v_and_b32_e32 v51, 0xffff0000, v51
	v_cvt_pk_bf16_f32 v50, v50, s0
	ds_write_b16 v81, v50 offset:9504
	v_mul_f32_e32 v50, v70, v51
	v_lshlrev_b32_e32 v73, 16, v52
	v_cvt_pk_bf16_f32 v50, v50, s0
	ds_write_b16 v81, v50 offset:9648
	v_mul_f32_e32 v50, v70, v73
	v_and_b32_e32 v52, 0xffff0000, v52
	v_cvt_pk_bf16_f32 v50, v50, s0
	ds_write_b16 v81, v50 offset:9792
	v_mul_f32_e32 v50, v70, v52
	v_lshlrev_b32_e32 v74, 16, v53
	v_cvt_pk_bf16_f32 v50, v50, s0
	ds_write_b16 v81, v50 offset:9936
	v_mul_f32_e32 v50, v70, v74
	v_and_b32_e32 v53, 0xffff0000, v53
	v_cvt_pk_bf16_f32 v50, v50, s0
	ds_write_b16 v81, v50 offset:10080
	v_mul_f32_e32 v50, v70, v53
	ds_bpermute_b32 v53, v136, v79
	ds_bpermute_b32 v38, v145, v79
	v_mfma_f32_16x16x32_bf16 v[54:57], v[20:23], v[66:69], v[54:57]
	ds_bpermute_b32 v39, v145, v113
	ds_bpermute_b32 v52, v137, v79
	s_waitcnt lgkmcnt(3)
	v_sub_f32_e32 v60, v53, v58
	s_waitcnt lgkmcnt(2)
	v_sub_f32_e32 v40, v53, v38
	v_mul_f32_e32 v60, 0x3fb8aa3b, v60
	v_mul_f32_e32 v40, 0x3fb8aa3b, v40
	v_mfma_f32_16x16x32_bf16 v[54:57], v[16:19], v[62:65], v[54:57]
	v_exp_f32_e32 v60, v60
	v_exp_f32_e32 v40, v40
	v_mul_f32_e32 v71, v70, v71
	v_cvt_pk_bf16_f32 v71, v71, s0
	v_add_u32_e32 v75, s21, v151
	s_nop 2
	v_mul_f32_e32 v54, v54, v60
	v_mul_f32_e32 v34, v34, v40
	v_mul_f32_e32 v54, v54, v59
	s_waitcnt lgkmcnt(1)
	v_mul_f32_e32 v34, v34, v39
	v_cvt_pk_bf16_f32 v54, v54, s0
	v_cvt_pk_bf16_f32 v34, v34, s0
	v_cvt_pk_bf16_f32 v50, v50, s0
	v_cndmask_b32_e64 v54, v54, 0, s[50:51]
	v_cndmask_b32_e64 v34, v34, 0, s[58:59]
	ds_write_b16 v75, v71
	ds_write_b16 v81, v50 offset:10224
	ds_write_b16 v160, v54 offset:54272
	s_waitcnt lgkmcnt(3)
; #define LAS __attribute__((address_space(3)))
; DI float bf2f(bf16_t b) { return __uint_as_float(((unsigned)b) << 16); }
; DI bf16_t f2bf(float f) { return (bf16_t)(pk2(f, 0.f) & 0xffffu); }
; #define LDS_BARRIER() do { asm volatile("s_waitcnt lgkmcnt(0)" ::: "memory"); __builtin_amdgcn_s_barrier(); asm volatile("" ::: "memory"); } while (0)
; #define MFMA16(a, b, c) __builtin_amdgcn_mfma_f32_16x16x32_bf16((a), (b), (c), 0, 0, 0)
; DI void ssd_scan(const Params& P, LAS unsigned char* lds) {
;     ...
;             for (int i = 0; i < 2; ++i) { const int nb = 2 * hb + i; f32x4 sc = {0.f, 0.f, 0.f, 0.f};
; #pragma unroll
;                 for (int ks = 0; ks < 4; ++ks) sc = MFMA16(ca[ks], bbf[i][ks], sc);
;                 const int s = 16 * nb + fr; const float cums = __shfl(cum, s), dts = __shfl(dtv, s);
; #pragma unroll
;                 for (int j = 0; j < 4; ++j) { const int t = 16 * mb + 4 * fq + j; Pm[t * 72 + s] = f2bf(s <= t ? sc[j] * __expf(cumt[j] - cums) * dts : 0.f); } }
;             LDS_BARRIER();
;             float dtn = dtv; bf16x8 cn[4];
; #pragma unroll
;             for (int ks = 0; ks < 4; ++ks) cn[ks] = ca[ks];
;             if (n + 1 < 32) SSD_LOAD(row0 + 64, dtn, cn);
;             f32x4 yi[2], ye[2];
; #pragma unroll
;             for (int i = 0; i < 2; ++i) { yi[i] = (f32x4){0.f, 0.f, 0.f, 0.f}; ye[i] = (f32x4){0.f, 0.f, 0.f, 0.f}; }
; #pragma unroll
;             for (int k2 = 0; k2 < 2; ++k2) { const bf16x8 am = *(const LAS bf16x8*)(Pm + (16 * mb + fr) * 72 + 32 * k2 + 8 * fq);
; #pragma unroll
;                 for (int i = 0; i < 2; ++i) { const bf16x8 bb = *(const LAS bf16x8*)(Xt + (16 * (2 * hb + i) + fr) * 72 + 32 * k2 + 8 * fq); yi[i] = MFMA16(am, bb, yi[i]); } }
; #pragma unroll
;             for (int ks = 0; ks < 4; ++ks)
; #pragma unroll
;                 for (int i = 0; i < 2; ++i) { const bf16x8 bb = *(const LAS bf16x8*)(Sb + (16 * (2 * hb + i) + fr) * 136 + 32 * ks + 8 * fq); ye[i] = MFMA16(ca[ks], bb, ye[i]); }
; #pragma unroll
;             for (int j = 0; j < 4; ++j) { const int tl = 16 * mb + 4 * fq + j, row = row0 + tl; const float ec = __expf(cumt[j]);
; #pragma unroll
;                 for (int i = 0; i < 2; ++i) { const int p = 16 * (2 * hb + i) + fr; const float xv = bf2f(Xt[p * 72 + tl]);
;                     YB[(size_t)row * 2048 + h * 64 + p] = f2bf(yi[i][j] + ec * ye[i][j] + dsk * xv); } }
	v_sub_f32_e32 v54, v52, v58
	ds_write_b16 v160, v34 offset:54304
	v_sub_f32_e32 v34, v52, v38
	v_mul_f32_e32 v54, 0x3fb8aa3b, v54
	v_mul_f32_e32 v34, 0x3fb8aa3b, v34
	v_exp_f32_e32 v54, v54
	v_exp_f32_e32 v34, v34
	ds_bpermute_b32 v51, v138, v79
	ds_bpermute_b32 v50, v139, v79
	v_mul_f32_e32 v54, v55, v54
	v_mul_f32_e32 v34, v35, v34
	v_mul_f32_e32 v54, v54, v59
	v_mul_f32_e32 v34, v34, v39
	v_cvt_pk_bf16_f32 v54, v54, s0
	v_cvt_pk_bf16_f32 v34, v34, s0
	v_cndmask_b32_e64 v54, v54, 0, s[52:53]
	v_cndmask_b32_e64 v34, v34, 0, s[60:61]
	ds_write_b16 v160, v54 offset:54416
	s_waitcnt lgkmcnt(2)
	v_sub_f32_e32 v54, v51, v58
	ds_write_b16 v160, v34 offset:54448
	v_sub_f32_e32 v34, v51, v38
	v_mul_f32_e32 v54, 0x3fb8aa3b, v54
	v_mul_f32_e32 v34, 0x3fb8aa3b, v34
	v_exp_f32_e32 v54, v54
	v_exp_f32_e32 v34, v34
	v_add_u32_e32 v55, v128, v147
	v_mov_b32_e32 v113, v25
	v_mul_f32_e32 v54, v56, v54
	v_mul_f32_e32 v34, v36, v34
	v_mul_f32_e32 v54, v54, v59
	v_mul_f32_e32 v34, v34, v39
	v_cvt_pk_bf16_f32 v54, v54, s0
	v_cvt_pk_bf16_f32 v34, v34, s0
	v_cndmask_b32_e64 v54, v54, 0, s[54:55]
	v_cndmask_b32_e64 v34, v34, 0, s[62:63]
	ds_write_b16 v160, v54 offset:54560
	s_waitcnt lgkmcnt(3)
	v_sub_f32_e32 v54, v50, v58
	ds_write_b16 v160, v34 offset:54592
	v_sub_f32_e32 v34, v50, v38
	v_mul_f32_e32 v54, 0x3fb8aa3b, v54
	v_mul_f32_e32 v34, 0x3fb8aa3b, v34
	v_exp_f32_e32 v54, v54
	v_exp_f32_e32 v34, v34
	v_mul_f32_e32 v54, v57, v54
	v_mul_f32_e32 v34, v37, v34
	v_mul_f32_e32 v54, v54, v59
	v_mul_f32_e32 v34, v34, v39
	v_cvt_pk_bf16_f32 v54, v54, s0
	v_cvt_pk_bf16_f32 v34, v34, s0
	v_cndmask_b32_e64 v54, v54, 0, s[56:57]
	v_cndmask_b32_e64 v34, v34, 0, s[64:65]
	ds_write_b16 v160, v54 offset:54704
	ds_write_b16 v160, v34 offset:54736
	s_waitcnt lgkmcnt(0)
	s_barrier
	ds_read_b128 v[34:37], v129 offset:54272
	v_add_u32_e32 v54, v128, v146
	ds_read_b128 v[38:41], v54 offset:63488
	ds_read_b128 v[42:45], v55 offset:63488
	s_waitcnt lgkmcnt(1)
	v_mfma_f32_16x16x32_bf16 v[38:41], v[34:37], v[38:41], 0
	s_waitcnt lgkmcnt(0)
	v_mfma_f32_16x16x32_bf16 v[42:45], v[34:37], v[42:45], 0
	ds_read_b128 v[46:49], v129 offset:54336
	ds_read_b128 v[34:37], v54 offset:63552
	s_waitcnt lgkmcnt(0)
	v_mfma_f32_16x16x32_bf16 v[34:37], v[46:49], v[34:37], v[38:41]
	s_nop 2
	ds_read_b128 v[38:41], v55 offset:63552
	s_waitcnt lgkmcnt(0)
	v_mfma_f32_16x16x32_bf16 v[38:41], v[46:49], v[38:41], v[42:45]
	s_nop 2
	ds_read_b128 v[42:45], v161
	ds_read_b128 v[46:49], v161 offset:4352
	s_waitcnt lgkmcnt(1)
	v_mfma_f32_16x16x32_bf16 v[42:45], v[30:33], v[42:45], 0
	s_waitcnt lgkmcnt(0)
	v_mfma_f32_16x16x32_bf16 v[30:33], v[30:33], v[46:49], 0
	ds_read_b128 v[46:49], v161 offset:64
	s_waitcnt lgkmcnt(0)
	v_mfma_f32_16x16x32_bf16 v[42:45], v[26:29], v[46:49], v[42:45]
	ds_read_b128 v[46:49], v161 offset:4416
	s_waitcnt lgkmcnt(0)
	v_mfma_f32_16x16x32_bf16 v[26:29], v[26:29], v[46:49], v[30:33]
	s_nop 2
	ds_read_b128 v[30:33], v161 offset:128
	s_waitcnt lgkmcnt(0)
	v_mfma_f32_16x16x32_bf16 v[30:33], v[20:23], v[30:33], v[42:45]
	s_nop 2
	ds_read_b128 v[42:45], v161 offset:4480
	s_waitcnt lgkmcnt(0)
	v_mfma_f32_16x16x32_bf16 v[20:23], v[20:23], v[42:45], v[26:29]
	s_nop 2
	ds_read_b128 v[26:29], v161 offset:192
	s_waitcnt lgkmcnt(0)
	v_mfma_f32_16x16x32_bf16 v[26:29], v[16:19], v[26:29], v[30:33]
	s_nop 2
	ds_read_b128 v[30:33], v161 offset:4544
	s_waitcnt lgkmcnt(0)
	v_mfma_f32_16x16x32_bf16 v[16:19], v[16:19], v[30:33], v[20:23]
	s_nop 2
	v_add_u32_e32 v22, v152, v146
	v_mul_f32_e32 v21, 0x3fb8aa3b, v53
	ds_read_b64 v[22:23], v22 offset:63488
	v_exp_f32_e32 v32, v21
	v_add_u32_e32 v20, s5, v124
	v_ashrrev_i32_e32 v21, 31, v20
	v_lshlrev_b64 v[20:21], 12, v[20:21]
	s_waitcnt lgkmcnt(0)
	v_lshlrev_b32_e32 v30, 16, v22
	v_fma_f32 v26, v32, v26, v34
	v_fmac_f32_e32 v26, v111, v30
	v_lshl_add_u64 v[20:21], v[104:105], 0, v[20:21]
	v_cvt_pk_bf16_f32 v26, v26, s0
	v_lshl_add_u64 v[20:21], v[20:21], 0, s[36:37]
	global_store_short v[20:21], v26, off
	v_add_u32_e32 v26, v152, v147
	ds_read_b64 v[30:31], v26 offset:63488
	v_fma_f32 v16, v32, v16, v38
	v_and_b32_e32 v22, 0xffff0000, v22
	s_waitcnt lgkmcnt(0)
; #define LAS __attribute__((address_space(3)))
; DI unsigned pk2(float lo, float hi) { const f32x2v v = {lo, hi}; const bf16x2v b = __builtin_convertvector(v, bf16x2v); return __builtin_bit_cast(unsigned, b); }
; DI float bf2f(bf16_t b) { return __uint_as_float(((unsigned)b) << 16); }
; DI bf16_t f2bf(float f) { return (bf16_t)(pk2(f, 0.f) & 0xffffu); }
; #define LDS_BARRIER() do { asm volatile("s_waitcnt lgkmcnt(0)" ::: "memory"); __builtin_amdgcn_s_barrier(); asm volatile("" ::: "memory"); } while (0)
; #define MFMA16(a, b, c) __builtin_amdgcn_mfma_f32_16x16x32_bf16((a), (b), (c), 0, 0, 0)
; DI void ssd_scan(const Params& P, LAS unsigned char* lds) {
;     ...
;             for (int j = 0; j < 4; ++j) { const int tl = 16 * mb + 4 * fq + j, row = row0 + tl; const float ec = __expf(cumt[j]);
; #pragma unroll
;                 for (int i = 0; i < 2; ++i) { const int p = 16 * (2 * hb + i) + fr; const float xv = bf2f(Xt[p * 72 + tl]);
;                     YB[(size_t)row * 2048 + h * 64 + p] = f2bf(yi[i][j] + ec * ye[i][j] + dsk * xv); } }
;             { const float ecl = __expf(cl);
; #pragma unroll
;               for (int i = 0; i < 4; ++i) Sacc[i] *= ecl; }
; #pragma unroll
;             for (int k2 = 0; k2 < 2; ++k2) { const bf16x8 am = *(const LAS bf16x8*)(BWt + (16 * wid + fr) * 72 + 32 * k2 + 8 * fq);
; #pragma unroll
;                 for (int i = 0; i < 4; ++i) { const bf16x8 bb = *(const LAS bf16x8*)(Xt + (16 * i + fr) * 72 + 32 * k2 + 8 * fq); Sacc[i] = MFMA16(am, bb, Sacc[i]); } }
; #pragma unroll
;             for (int i = 0; i < 4; ++i) { u32x2 w; w.x = pk2(Sacc[i][0], Sacc[i][1]); w.y = pk2(Sacc[i][2], Sacc[i][3]); *(LAS u32x2*)(Sbn + (16 * i + fr) * 136 + 16 * wid + 4 * fq) = w; }
;             dtv = dtn;
; #pragma unroll
;             for (int ks = 0; ks < 4; ++ks) ca[ks] = cn[ks];
;         }
;     ...
;         float* SO = P.out + OUT_SSMP + ((size_t)(b * 32 + h) * 64) * 128;
; #pragma unroll
;         for (int i = 0; i < 4; ++i) *(f32x4*)(SO + (size_t)(16 * i + fr) * 128 + 16 * wid + 4 * fq) = Sacc[i];
;         LDS_BARRIER();
;     }
	v_lshlrev_b32_e32 v26, 16, v30
	v_fmac_f32_e32 v16, v111, v26
	v_cvt_pk_bf16_f32 v16, v16, s0
	global_store_short v[20:21], v16, off offset:32
	v_mul_f32_e32 v16, 0x3fb8aa3b, v52
	v_exp_f32_e32 v16, v16
	v_add_u32_e32 v20, s5, v142
	v_ashrrev_i32_e32 v21, 31, v20
	v_lshlrev_b64 v[20:21], 12, v[20:21]
	v_fma_f32 v26, v16, v27, v35
	v_fmac_f32_e32 v26, v111, v22
	v_lshl_add_u64 v[20:21], v[104:105], 0, v[20:21]
	v_cvt_pk_bf16_f32 v22, v26, s0
	v_lshl_add_u64 v[20:21], v[20:21], 0, s[36:37]
	global_store_short v[20:21], v22, off
	v_and_b32_e32 v22, 0xffff0000, v30
	v_fma_f32 v16, v16, v17, v39
	v_fmac_f32_e32 v16, v111, v22
	v_cvt_pk_bf16_f32 v16, v16, s0
	v_mul_f32_e32 v17, 0x3fb8aa3b, v51
	global_store_short v[20:21], v16, off offset:32
	v_exp_f32_e32 v20, v17
	v_add_u32_e32 v16, s5, v143
	v_ashrrev_i32_e32 v17, 31, v16
	v_lshlrev_b32_e32 v21, 16, v23
	v_fma_f32 v22, v20, v28, v36
	v_lshlrev_b64 v[16:17], 12, v[16:17]
	v_fmac_f32_e32 v22, v111, v21
	v_lshl_add_u64 v[16:17], v[104:105], 0, v[16:17]
	v_cvt_pk_bf16_f32 v21, v22, s0
	v_lshl_add_u64 v[16:17], v[16:17], 0, s[36:37]
	global_store_short v[16:17], v21, off
	v_lshlrev_b32_e32 v21, 16, v31
	v_fma_f32 v18, v20, v18, v40
	v_fmac_f32_e32 v18, v111, v21
	v_cvt_pk_bf16_f32 v18, v18, s0
	global_store_short v[16:17], v18, off offset:32
	v_mul_f32_e32 v17, 0x3fb8aa3b, v50
	v_exp_f32_e32 v18, v17
	v_add_u32_e32 v16, s5, v144
	v_ashrrev_i32_e32 v17, 31, v16
	v_and_b32_e32 v20, 0xffff0000, v23
	v_fmac_f32_e32 v37, v18, v29
	v_lshlrev_b64 v[16:17], 12, v[16:17]
	v_fmac_f32_e32 v37, v111, v20
	v_lshl_add_u64 v[16:17], v[104:105], 0, v[16:17]
	v_cvt_pk_bf16_f32 v20, v37, s0
	v_lshl_add_u64 v[16:17], v[16:17], 0, s[36:37]
	global_store_short v[16:17], v20, off
	v_and_b32_e32 v20, 0xffff0000, v31
	v_fmac_f32_e32 v41, v18, v19
	v_fmac_f32_e32 v41, v111, v20
	v_cvt_pk_bf16_f32 v18, v41, s0
	global_store_short v[16:17], v18, off offset:32
	v_mul_f32_e32 v16, 0x3fb8aa3b, v78
	v_exp_f32_e32 v16, v16
	v_add_u32_e32 v26, v128, v149
	ds_read_b128 v[20:23], v26 offset:63488
	s_ashr_i32 s5, s4, 31
	v_pk_mul_f32 v[2:3], v[2:3], v[16:17] op_sel_hi:[1,0]
	v_pk_mul_f32 v[0:1], v[0:1], v[16:17] op_sel_hi:[1,0]
	v_pk_mul_f32 v[6:7], v[6:7], v[16:17] op_sel_hi:[1,0]
	v_pk_mul_f32 v[4:5], v[4:5], v[16:17] op_sel_hi:[1,0]
	v_pk_mul_f32 v[14:15], v[14:15], v[16:17] op_sel_hi:[1,0]
	v_pk_mul_f32 v[12:13], v[12:13], v[16:17] op_sel_hi:[1,0]
	v_pk_mul_f32 v[10:11], v[10:11], v[16:17] op_sel_hi:[1,0]
	v_pk_mul_f32 v[8:9], v[8:9], v[16:17] op_sel_hi:[1,0]
	ds_read_b128 v[16:19], v153
	s_waitcnt lgkmcnt(0)
	v_mfma_f32_16x16x32_bf16 v[0:3], v[16:19], v[20:23], v[0:3]
	ds_read_b128 v[20:23], v162 offset:63488
	s_lshl_b64 s[16:17], s[4:5], 15
	v_mov_b32_e32 v111, v25
	s_waitcnt lgkmcnt(0)
	v_mfma_f32_16x16x32_bf16 v[4:7], v[16:19], v[20:23], v[4:7]
	ds_read_b128 v[20:23], v163 offset:63488
	s_waitcnt lgkmcnt(0)
	v_mfma_f32_16x16x32_bf16 v[12:15], v[16:19], v[20:23], v[12:15]
	ds_read_b128 v[20:23], v164 offset:63488
	s_waitcnt lgkmcnt(0)
	v_mfma_f32_16x16x32_bf16 v[8:11], v[16:19], v[20:23], v[8:11]
	ds_read_b128 v[16:19], v153 offset:64
	ds_read_b128 v[20:23], v26 offset:63552
	s_load_dwordx2 s[14:15], s[0:1], 0x150
	s_waitcnt lgkmcnt(0)
	s_add_u32 s5, s14, s16
	v_mfma_f32_16x16x32_bf16 v[0:3], v[16:19], v[20:23], v[0:3]
	ds_read_b128 v[20:23], v162 offset:63552
	s_addc_u32 s13, s15, s17
	s_add_u32 s14, s5, s22
	s_waitcnt lgkmcnt(0)
	v_mfma_f32_16x16x32_bf16 v[4:7], v[16:19], v[20:23], v[4:7]
	ds_read_b128 v[20:23], v163 offset:63552
	s_addc_u32 s15, s13, 0
	s_mov_b32 s5, 0x8ff8000
	s_waitcnt lgkmcnt(0)
	v_mfma_f32_16x16x32_bf16 v[12:15], v[16:19], v[20:23], v[12:15]
	ds_read_b128 v[20:23], v164 offset:63552
	s_waitcnt lgkmcnt(0)
	v_mfma_f32_16x16x32_bf16 v[8:11], v[16:19], v[20:23], v[8:11]
	v_cvt_pk_bf16_f32 v16, v0, v1
	v_cvt_pk_bf16_f32 v17, v2, v3
	v_add_u32_e32 v18, v154, v150
	ds_write_b64 v18, v[16:17] offset:18432
	v_cvt_pk_bf16_f32 v16, v4, v5
	v_cvt_pk_bf16_f32 v17, v6, v7
	ds_write_b64 v18, v[16:17] offset:22784
	v_cvt_pk_bf16_f32 v16, v12, v13
	v_cvt_pk_bf16_f32 v17, v14, v15
	ds_write_b64 v18, v[16:17] offset:27136
	v_cvt_pk_bf16_f32 v16, v8, v9
	v_cvt_pk_bf16_f32 v17, v10, v11
	ds_write_b64 v18, v[16:17] offset:31488
	v_lshl_add_u64 v[16:17], s[14:15], 0, v[110:111]
	v_lshl_add_u64 v[16:17], v[16:17], 0, v[112:113]
	v_add_co_u32_e32 v18, vcc, s5, v16
	s_mov_b32 s5, 0x8ffa000
	s_nop 0
	v_addc_co_u32_e32 v19, vcc, 0, v17, vcc
	global_store_dwordx4 v[18:19], v[0:3], off
	v_readlane_b32 s14, v255, 13
	v_readlane_b32 s15, v255, 14
	v_add_co_u32_e32 v0, vcc, s5, v16
	s_mov_b32 s5, 0x8ffc000
	s_nop 0
	v_addc_co_u32_e32 v1, vcc, 0, v17, vcc
	global_store_dwordx4 v[0:1], v[4:7], off
	v_add_co_u32_e32 v0, vcc, s5, v16
	s_nop 1
	v_addc_co_u32_e32 v1, vcc, 0, v17, vcc
	global_store_dwordx4 v[0:1], v[12:15], off
	v_add_co_u32_e32 v0, vcc, 0x8ffe000, v16
	s_nop 1
	v_addc_co_u32_e32 v1, vcc, 0, v17, vcc
	global_store_dwordx4 v[0:1], v[8:11], off
	s_waitcnt lgkmcnt(0)
	s_barrier
	s_load_dword s5, s[14:15], 0x0
	s_waitcnt lgkmcnt(0)
	s_add_i32 s4, s5, s4
	s_cmpk_gt_i32 s4, 0xff
	s_cbranch_scc0 .LBB0_174
